# attention / scan work-queue phases: static priority raise for waves 4-7 of every workgroup
# baseline (speedup 1.0000x reference)
; #define LAS __attribute__((address_space(3)))
; __device__ __forceinline__ int next_item(unsigned* ctr, LAS unsigned* slot) {
;     __syncthreads();
;     if (threadIdx.x == 0) *slot = atomicAdd(ctr, 1u);
;     __syncthreads();
;     return (int)*slot;
; __global__ void __launch_bounds__(512) hymba_fwd(Args a) {
;     ...
;             for (;;) {
;                 const int idx = next_item(ctl + pb + 1, qslot);
;                 if (idx >= 256 + 1024) break;
.LBB0_211:
	s_waitcnt lgkmcnt(0)
	s_barrier
	v_readfirstlane_b32 s100, v210
	s_nop 3
	s_lshr_b32 s100, s100, 6
	s_cmp_lt_u32 s100, 4
	s_cbranch_scc1 .Lprio_a_done
	s_setprio 1
.Lprio_a_done:
	s_mov_b64 s[0:1], exec
	v_readlane_b32 s2, v253, 0
	v_readlane_b32 s3, v253, 1
	s_and_b64 s[2:3], s[0:1], s[2:3]
	s_mov_b64 exec, s[2:3]
	s_cbranch_execz .LBB0_213
	v_cmp_ne_u32_e32 vcc, -1, v255
	s_nop 1
	s_cbranch_vccnz .Lnx_a_have
	v_readlane_b32 s2, v252, 3
	v_readlane_b32 s3, v252, 4
	s_waitcnt vmcnt(0)
	s_nop 0
	v_mov_b64_e32 v[2:3], s[2:3]
	global_atomic_add v255, v[2:3], v213, off offset:8 sc0
	s_waitcnt vmcnt(0)

; __device__ __forceinline__ void xbar(unsigned* ctl, unsigned k, unsigned x, unsigned nloc, unsigned nx) {
;     asm volatile("s_waitcnt vmcnt(0)" ::: "memory");
;     __syncthreads();
;     if (threadIdx.x == 0) {
;         const unsigned old = __hip_atomic_fetch_add(ctl + 2048 + 64 * x, 1u, __ATOMIC_RELAXED, __HIP_MEMORY_SCOPE_AGENT);
;         if (old + 1u == nloc * (k + 1u)) {
;             __builtin_amdgcn_fence(__ATOMIC_RELEASE, "agent");
;             __hip_atomic_fetch_add(ctl + 3072, 1u, __ATOMIC_RELAXED, __HIP_MEMORY_SCOPE_AGENT);
;         }
.LBB0_322:
	s_setprio 0
	s_waitcnt vmcnt(0)
	s_waitcnt lgkmcnt(0)
	s_barrier
	s_mov_b64 s[0:1], exec
	v_readlane_b32 s2, v253, 0
	v_readlane_b32 s3, v253, 1
	v_readlane_b32 s80, v253, 6
	v_readlane_b32 s10, v254, 42
	v_readlane_b32 s12, v254, 50
	v_readlane_b32 s14, v254, 52
	s_and_b64 s[2:3], s[0:1], s[2:3]
	v_readlane_b32 s73, v254, 35
	v_readlane_b32 s81, v253, 7
	v_readlane_b32 s82, v253, 8
	v_readlane_b32 s83, v253, 9
	v_readlane_b32 s77, v254, 60
	v_readlane_b32 s84, v254, 63
	v_readlane_b32 s11, v254, 43
	v_readlane_b32 s13, v254, 51
	v_readlane_b32 s15, v254, 53
	v_readlane_b32 s16, v254, 56
	v_readlane_b32 s17, v254, 57
	v_readlane_b32 s85, v252, 0
	s_mov_b64 exec, s[2:3]
	s_cbranch_execz .LBB0_328
	v_readlane_b32 s2, v253, 49
	v_readlane_b32 s8, v252, 1
	v_readlane_b32 s3, v253, 50
	v_readlane_b32 s9, v252, 2
	s_add_u32 s2, s8, s2
	s_addc_u32 s3, s9, s3
	v_mov_b32_e32 v0, s2
	s_waitcnt vmcnt(0)
	v_add_co_u32_e32 v2, vcc, 0x2000, v0
	v_mov_b32_e32 v0, s3
	s_nop 0
	v_addc_co_u32_e32 v3, vcc, 0, v0, vcc
	global_atomic_add v0, v[2:3], v213, off sc0
	s_mul_i32 s4, s77, 6
	s_add_i32 s4, s4, 2
	v_readlane_b32 s2, v253, 10
	s_mul_i32 s2, s4, s2
	s_waitcnt vmcnt(0) lgkmcnt(0)
	v_add_u32_e32 v0, 1, v0
	v_cmp_eq_u32_e32 vcc, s2, v0
	s_and_saveexec_b64 s[2:3], vcc
	s_cbranch_execz .LBB0_325
	v_mov_b32_e32 v0, s8
	v_add_co_u32_e32 v2, vcc, 0x3000, v0
	v_mov_b32_e32 v0, s9
	s_nop 0
	v_addc_co_u32_e32 v3, vcc, 0, v0, vcc
	buffer_wbl2 sc1
	global_atomic_add v[2:3], v213, off

; #define LAS __attribute__((address_space(3)))
; __device__ __forceinline__ int next_item(unsigned* ctr, LAS unsigned* slot) {
;     __syncthreads();
;     if (threadIdx.x == 0) *slot = atomicAdd(ctr, 1u);
;     __syncthreads();
;     return (int)*slot;
; __global__ void __launch_bounds__(512) hymba_fwd(Args a) {
;     ...
;                 for (;;) {
;                     const int idx = next_item(ctl + pb + 3 + 16 * rep, qslot);
.LBB0_470:
	s_barrier
	v_readfirstlane_b32 s100, v210
	s_nop 3
	s_lshr_b32 s100, s100, 6
	s_cmp_lt_u32 s100, 4
	s_cbranch_scc1 .Lprio_b_done
	s_setprio 1
.Lprio_b_done:
	s_mov_b64 s[0:1], exec
	v_readlane_b32 s2, v253, 0
	v_readlane_b32 s3, v253, 1
	s_and_b64 s[2:3], s[0:1], s[2:3]
	s_mov_b64 exec, s[2:3]
	s_cbranch_execz .LBB0_472
	v_readlane_b32 s2, v254, 19
	s_nop 1
	v_mov_b32_e32 v2, s2
	s_waitcnt lgkmcnt(0)
	ds_write_b32 v2, v255

; __device__ __forceinline__ void xbar(unsigned* ctl, unsigned k, unsigned x, unsigned nloc, unsigned nx) {
;     asm volatile("s_waitcnt vmcnt(0)" ::: "memory");
;     __syncthreads();
;     if (threadIdx.x == 0) {
;         const unsigned old = __hip_atomic_fetch_add(ctl + 2048 + 64 * x, 1u, __ATOMIC_RELAXED, __HIP_MEMORY_SCOPE_AGENT);
;         if (old + 1u == nloc * (k + 1u)) {
;             __builtin_amdgcn_fence(__ATOMIC_RELEASE, "agent");
;             __hip_atomic_fetch_add(ctl + 3072, 1u, __ATOMIC_RELAXED, __HIP_MEMORY_SCOPE_AGENT);
.LBB0_576:
	s_setprio 0
	s_add_i32 s6, s84, 5
	s_cmp_ge_i32 s6, s71
	s_cbranch_scc1 .LBB0_586
	s_waitcnt vmcnt(0)
	s_waitcnt lgkmcnt(0)
	s_barrier
	s_mov_b64 s[0:1], exec
	v_readlane_b32 s2, v253, 0
	v_readlane_b32 s3, v253, 1
	s_and_b64 s[2:3], s[0:1], s[2:3]
	s_mov_b32 s55, 0xf800000
	s_mov_b32 s37, 0x7f800000
	s_movk_i32 s38, 0x5ff
	s_mov_b32 s40, 0xbfb8aa3b
	s_mov_b64 exec, s[2:3]
	s_cbranch_execz .LBB0_585
	s_mov_b64 s[4:5], exec
	v_mbcnt_lo_u32_b32 v0, s4, 0
	v_mbcnt_hi_u32_b32 v0, s5, v0
	v_cmp_eq_u32_e32 vcc, 0, v0
	s_and_saveexec_b64 s[2:3], vcc
	s_cbranch_execz .LBB0_580
	s_bcnt1_i32_b64 s4, s[4:5]
	v_mov_b32_e32 v2, s4
	v_readlane_b32 s4, v253, 51
	v_readlane_b32 s5, v253, 52
	s_nop 4
	global_atomic_add v2, v1, v2, s[4:5] sc0
